# scan: the two counter waits merged into one thread-0 section (one workgroup barrier less before the scan)
# baseline (speedup 1.0000x reference)
; __device__ __forceinline__ void grp_wait(unsigned* c, unsigned target) {
;     if (threadIdx.x == 0) {
;         unsigned sp = 0;
;         while (__hip_atomic_load(c, __ATOMIC_RELAXED, __HIP_MEMORY_SCOPE_AGENT) < target) { __builtin_amdgcn_s_sleep(2); if (++sp > (1u << 22)) break; }
;         __builtin_amdgcn_fence(__ATOMIC_ACQUIRE, "agent");
;         asm volatile("s_waitcnt vmcnt(0)" ::: "memory");
;     }
;     __syncthreads();
; }
; __global__ void __launch_bounds__(512, 2) mk_fwd(Args args) {
;     ...
;             grp_wait(cntA + 64 * (vb >> 5), 32u); grp_wait(cntA + 64 * ((vb >> 5) + 8), 32u);
.LBB0_270:
	s_mov_b32 s1, 0x400001
	v_mov_b32_e32 v0, 0
	s_branch .LBB0_273
